# work-queue granularity: attention q blocks with qb >= 8 split into two key-range halves (was qb >= 14), items ordered by nominal half size, so no single unsplit heavy item pins the phase
# speedup vs baseline: 1.0140x; 1.0140x over previous
; __device__ __forceinline__ void item_decode(int item, int& qb, int& bh, int& nh, int& half) {
;     constexpr int GQ[16] = {13, 12, 11, 10, 9, 8, 15, 7, 14, 6, 5, 4, 3, 2, 1, 0};
;     int base = 0; qb = 0; nh = 1; half = 0; bh = 0;
; #pragma unroll
;     for (int g = 0; g < 16; ++g) { const int q = GQ[g], n = q >= 14 ? 2 : 1, cnt = 32 * n; if (item >= base && item < base + cnt) { const int r = item - base; qb = q; nh = n; bh = r % 32; half = n == 2 ? 1 - r / 32 : 0; } base += cnt; }
; }
; __device__ __forceinline__ void attn_phase(const bf16_t* FQ, const bf16_t* FK, const bf16_t* FV, const float* cum, const float* norms, bf16_t* Y, unsigned* qctr, unsigned* flags, float* parts, lptr lds, int tid_) {
;     ...
;         const int item = sh[0];
;         if (item >= N_ITEMS) break;
;         int qb, bh, nh, half; item_decode(item, qb, bh, nh, half);
.LBB0_828:
	s_or_b64 exec, exec, s[0:1]
	v_mov_b32_e32 v1, s62
	s_waitcnt lgkmcnt(0)
	s_barrier
	ds_read_b32 v1, v1
	s_movk_i32 s0, 0x2ff
	s_waitcnt lgkmcnt(0)
	v_cmp_lt_i32_e32 vcc, s0, v1
	v_readfirstlane_b32 s6, v1
	s_mov_b64 s[0:1], -1
	s_cbranch_vccnz .LBB0_823
	s_mov_b32 s7, s6
	s_mov_b32 s74, 15
	s_mov_b32 s11, 2
	s_cmp_lt_u32 s7, 64
	s_cbranch_scc1 .Litem_decoded
	s_sub_u32 s7, s7, 64
	s_mov_b32 s74, 7
	s_mov_b32 s11, 1
	s_cmp_lt_u32 s7, 32
	s_cbranch_scc1 .Litem_decoded
	s_sub_u32 s7, s7, 32
	s_mov_b32 s74, 14
	s_mov_b32 s11, 2
	s_cmp_lt_u32 s7, 64
	s_cbranch_scc1 .Litem_decoded
	s_sub_u32 s7, s7, 64
	s_mov_b32 s74, 13
	s_mov_b32 s11, 2
	s_cmp_lt_u32 s7, 64
	s_cbranch_scc1 .Litem_decoded
	s_sub_u32 s7, s7, 64
	s_mov_b32 s74, 6
	s_mov_b32 s11, 1
	s_cmp_lt_u32 s7, 32
	s_cbranch_scc1 .Litem_decoded
	s_sub_u32 s7, s7, 32
	s_mov_b32 s74, 12
	s_mov_b32 s11, 2
	s_cmp_lt_u32 s7, 64
	s_cbranch_scc1 .Litem_decoded
	s_sub_u32 s7, s7, 64
	s_mov_b32 s74, 11
	s_mov_b32 s11, 2
	s_cmp_lt_u32 s7, 64
	s_cbranch_scc1 .Litem_decoded
	s_sub_u32 s7, s7, 64
	s_mov_b32 s74, 5
	s_mov_b32 s11, 1
	s_cmp_lt_u32 s7, 32
	s_cbranch_scc1 .Litem_decoded
	s_sub_u32 s7, s7, 32
	s_mov_b32 s74, 10
	s_mov_b32 s11, 2
	s_cmp_lt_u32 s7, 64
	s_cbranch_scc1 .Litem_decoded
	s_sub_u32 s7, s7, 64
	s_mov_b32 s74, 9
	s_mov_b32 s11, 2
	s_cmp_lt_u32 s7, 64
	s_cbranch_scc1 .Litem_decoded
	s_sub_u32 s7, s7, 64
	s_mov_b32 s74, 4
	s_mov_b32 s11, 1
	s_cmp_lt_u32 s7, 32
	s_cbranch_scc1 .Litem_decoded
	s_sub_u32 s7, s7, 32
	s_mov_b32 s74, 8
	s_mov_b32 s11, 2
	s_cmp_lt_u32 s7, 64
	s_cbranch_scc1 .Litem_decoded
	s_sub_u32 s7, s7, 64
	s_mov_b32 s74, 3
	s_mov_b32 s11, 1
	s_cmp_lt_u32 s7, 32
	s_cbranch_scc1 .Litem_decoded
	s_sub_u32 s7, s7, 32
	s_mov_b32 s74, 2
	s_mov_b32 s11, 1
	s_cmp_lt_u32 s7, 32
	s_cbranch_scc1 .Litem_decoded
	s_sub_u32 s7, s7, 32
	s_mov_b32 s74, 1
	s_mov_b32 s11, 1
	s_cmp_lt_u32 s7, 32
	s_cbranch_scc1 .Litem_decoded
	s_sub_u32 s7, s7, 32
	s_mov_b32 s74, 0
	s_mov_b32 s11, 1
.Litem_decoded:
	s_and_b32 s96, s7, 31
	s_lshr_b32 s10, s7, 5
	s_xor_b32 s10, s10, 1
	s_cmp_eq_u32 s11, 2
	s_cselect_b32 s10, s10, 0
